# grid barrier WAIT poll back-off s_sleep 6 instead of 1 (on top of v23)
# speedup vs baseline: 1.0034x; 1.0034x over previous
; __device__ __forceinline__ unsigned xb_ld(unsigned* p)              { return __hip_atomic_load(p, __ATOMIC_RELAXED, __HIP_MEMORY_SCOPE_AGENT); }
; #define XB_SPIN(cond, bar) do { unsigned _sp = 0; while (cond) { __builtin_amdgcn_s_sleep(1); \
;     if ((++_sp & 255u) == 0u) { if (xb_ld(&(bar)[XB_TMO])) break; if (_sp > XB_SPIN_CAP) { atomicAdd(&(bar)[XB_TMO], 1u); break; } } } } while (0)
; __device__ __forceinline__ bool xb_thread0(int wave) { return wave == 0 && hw_lane() == 0; }
; __device__ __forceinline__ void xcd_barrier_wait(const XcdBarrier& b) {
;     if (xb_thread0(b.wave)) {
;         const unsigned g = b.st[2];
;         XB_SPIN(xb_ld(&b.bar[XB_TOPGEN]) <= g, b.bar);
;         __builtin_amdgcn_fence(__ATOMIC_ACQUIRE, "agent");
;         asm volatile("s_waitcnt vmcnt(0)" ::: "memory");
;     }
;     __syncthreads();
; }
.LBB0_202:
	s_and_b32 s6, s10, 0xff
	s_mov_b64 s[4:5], -1
	s_cmp_lg_u32 s6, 0
	s_mov_b64 s[8:9], -1
	s_sleep 6
	s_cbranch_scc0 .LBB0_205
	s_and_b64 vcc, exec, s[8:9]
	s_cbranch_vccz .LBB0_201

.LBB0_634:
	s_and_b32 s10, s16, 0xff
	s_mov_b64 s[6:7], -1
	s_cmp_lg_u32 s10, 0
	s_mov_b64 s[14:15], -1
	s_sleep 6
	s_cbranch_scc0 .LBB0_637
	s_and_b64 vcc, exec, s[14:15]
	s_cbranch_vccz .LBB0_633

.LBB0_729:
	s_and_b32 s4, s8, 0xff
	s_mov_b64 s[2:3], -1
	s_cmp_lg_u32 s4, 0
	s_mov_b64 s[6:7], -1
	s_sleep 6
	s_cbranch_scc0 .LBB0_732
	s_and_b64 vcc, exec, s[6:7]
	s_cbranch_vccz .LBB0_728
